# mix2->out-proj grid barrier replaced by per-row-panel readiness counters (retention outputs written through, out units start as soon as their 8 producer workgroups finish)
# speedup vs baseline: 1.0153x; 1.0153x over previous
.LBB0_312:
	s_cmp_le_u32 s30, s82
	s_cbranch_scc1 .LBB0_360
	s_cmp_eq_u32 s30, 2
	s_cbranch_scc1 .Lskip_gbar
	s_cmp_eq_u32 s30, 9
	s_cbranch_scc1 .Lskip_gbar
	s_cmp_eq_u32 s30, 11
	s_cbranch_scc1 .Lskip_gbar
	s_cmp_eq_u32 s30, 7
	s_cbranch_scc1 .Lskip_gbar
	s_cmp_eq_u32 s30, 16
	s_cbranch_scc1 .Lskip_gbar
	s_cmp_lg_u32 s30, 18
	s_cbranch_scc1 .Lno_skip_gbar

.LBB0_393:
	s_or_b64 exec, exec, s[20:21]
	v_mov_b64_e32 v[78:79], v[46:47]
	v_mov_b64_e32 v[70:71], v[50:51]
	v_mov_b64_e32 v[82:83], v[54:55]
	v_mov_b64_e32 v[74:75], v[58:59]
	v_mov_b64_e32 v[40:41], v[60:61]
	s_andn2_b64 vcc, exec, s[18:19]
	s_mov_b32 s24, s3
	v_mov_b64_e32 v[76:77], v[44:45]
	v_mov_b64_e32 v[68:69], v[48:49]
	v_mov_b64_e32 v[80:81], v[52:53]
	v_mov_b64_e32 v[72:73], v[56:57]
	v_mov_b64_e32 v[42:43], v[62:63]
	v_mov_b32_e32 v36, v64
	v_mov_b32_e32 v37, v65
	v_mov_b32_e32 v38, v66
	v_mov_b32_e32 v39, v67
	s_waitcnt vmcnt(0) lgkmcnt(0)
	s_barrier
	s_cmp_lg_u32 s86, 0
	s_cbranch_scc1 .Lm2_sig_done
	s_lshr_b32 s3, s24, 8
	s_cmp_eq_u32 s3, 2
	s_cbranch_scc1 .Lm2_sig_b0
	s_cmp_eq_u32 s3, 4
	s_cbranch_scc1 .Lm2_sig_b1
	s_cmp_eq_u32 s3, 5
	s_cbranch_scc0 .Lm2_sig_done
	s_movk_i32 s3, 0x3f00
	s_branch .Lm2_sig_do
.Lm2_sig_b0:
	s_and_b32 s3, s55, 0x7f
	s_lshr_b32 s3, s3, 2
	s_lshl_b32 s3, s3, 2
	s_addk_i32 s3, 0x3e00
	s_branch .Lm2_sig_do
.Lm2_sig_b1:
	s_and_b32 s3, s55, 0x7f
	s_lshr_b32 s3, s3, 2
	s_lshl_b32 s3, s3, 2
	s_addk_i32 s3, 0x3e80
.Lm2_sig_do:
	v_mov_b32_e32 v1, s3
	s_mov_b64 exec, 1
	global_atomic_add v1, v223, s[90:91]
	s_mov_b64 exec, -1
.Lm2_sig_done:
	s_cbranch_vccz .LBB0_418

.LBB0_414:
	s_or_b64 exec, exec, s[20:21]
	s_waitcnt lgkmcnt(0)
	s_barrier
	ds_read_b64 v[80:81], v154
	s_brev_b32 s20, 60
	s_ashr_i32 s26, s25, 2
	s_lshl_b32 s25, s26, 13
	s_waitcnt lgkmcnt(0)
	v_pk_add_f32 v[72:73], v[72:73], v[80:81]
	s_nop 0
	v_pk_mul_f32 v[72:73], v[72:73], s[20:21] op_sel_hi:[1,0]
	s_nop 0
	v_fma_f32 v73, -v72, v72, v73
	v_max_f32_e32 v73, 0, v73
	v_add_f32_e32 v73, 0x3727c5ac, v73
	v_mul_f32_e32 v80, 0x4b800000, v73
	v_cmp_gt_f32_e64 s[44:45], s35, v73
	v_sub_f32_e32 v81, v92, v72
	v_sub_f32_e32 v68, v68, v72
	v_cndmask_b32_e64 v73, v73, v80, s[44:45]
	v_rsq_f32_e32 v73, v73
	v_sub_f32_e32 v80, v88, v72
	v_mul_f32_e32 v82, 0x45800000, v73
	v_cndmask_b32_e64 v73, v73, v82, s[44:45]
	v_mul_f32_e32 v80, v80, v73
	s_waitcnt vmcnt(0)
	v_mul_f32_e32 v80, v113, v80
	v_bfe_u32 v82, v80, 16, 1
	v_mul_f32_e32 v81, v81, v73
	v_add3_u32 v80, v80, v82, s34
	ds_write_b16_d16_hi v171, v80
	v_mul_f32_e32 v80, v3, v81
	v_bfe_u32 v81, v80, 16, 1
	v_add3_u32 v80, v80, v81, s34
	ds_write_b16_d16_hi v171, v80 offset:32
	v_sub_f32_e32 v80, v100, v72
	v_mul_f32_e32 v80, v80, v73
	v_mul_f32_e32 v68, v68, v73
	v_mul_f32_e32 v80, v2, v80
	v_mul_f32_e32 v68, v1, v68
	v_bfe_u32 v81, v80, 16, 1
	v_bfe_u32 v72, v68, 16, 1
	v_add3_u32 v80, v80, v81, s34
	v_add3_u32 v68, v68, v72, s34
	ds_write_b16_d16_hi v171, v80 offset:64
	ds_write_b16_d16_hi v171, v68 offset:96
	ds_read_b64 v[72:73], v155
	s_waitcnt lgkmcnt(0)
	v_pk_add_f32 v[72:73], v[74:75], v[72:73]
	s_nop 0
	v_pk_mul_f32 v[72:73], v[72:73], s[20:21] op_sel_hi:[1,0]
	s_nop 0
	v_fma_f32 v68, -v72, v72, v73
	v_max_f32_e32 v68, 0, v68
	v_add_f32_e32 v68, 0x3727c5ac, v68
	v_mul_f32_e32 v73, 0x4b800000, v68
	v_cmp_gt_f32_e64 s[44:45], s35, v68
	v_sub_f32_e32 v69, v69, v72
	s_nop 0
	v_cndmask_b32_e64 v68, v68, v73, s[44:45]
	v_rsq_f32_e32 v68, v68
	s_nop 0
	v_mul_f32_e32 v73, 0x45800000, v68
	v_cndmask_b32_e64 v68, v68, v73, s[44:45]
	v_sub_f32_e32 v73, v89, v72
	v_mul_f32_e32 v73, v73, v68
	v_mul_f32_e32 v73, v113, v73
	v_bfe_u32 v74, v73, 16, 1
	v_add3_u32 v73, v73, v74, s34
	ds_write_b16_d16_hi v171, v73 offset:272
	v_sub_f32_e32 v73, v93, v72
	v_mul_f32_e32 v73, v73, v68
	v_mul_f32_e32 v73, v3, v73
	v_bfe_u32 v74, v73, 16, 1
	v_add3_u32 v73, v73, v74, s34
	ds_write_b16_d16_hi v171, v73 offset:304
	v_sub_f32_e32 v73, v101, v72
	v_mul_f32_e32 v73, v73, v68
	v_mul_f32_e32 v68, v69, v68
	v_mul_f32_e32 v73, v2, v73
	v_mul_f32_e32 v68, v1, v68
	v_bfe_u32 v74, v73, 16, 1
	v_bfe_u32 v69, v68, 16, 1
	v_add3_u32 v73, v73, v74, s34
	v_add3_u32 v68, v68, v69, s34
	ds_write_b16_d16_hi v171, v73 offset:336
	ds_write_b16_d16_hi v171, v68 offset:368
	ds_read_b64 v[68:69], v156
	s_waitcnt lgkmcnt(0)
	v_pk_add_f32 v[68:69], v[76:77], v[68:69]
	s_nop 0
	v_pk_mul_f32 v[68:69], v[68:69], s[20:21] op_sel_hi:[1,0]
	s_nop 0
	v_fma_f32 v69, -v68, v68, v69
	v_max_f32_e32 v69, 0, v69
	v_add_f32_e32 v69, 0x3727c5ac, v69
	v_mul_f32_e32 v72, 0x4b800000, v69
	v_cmp_gt_f32_e64 s[44:45], s35, v69
	s_nop 1
	v_cndmask_b32_e64 v69, v69, v72, s[44:45]
	v_rsq_f32_e32 v69, v69
	s_nop 0
	v_mul_f32_e32 v72, 0x45800000, v69
	v_cndmask_b32_e64 v69, v69, v72, s[44:45]
	v_sub_f32_e32 v72, v90, v68
	v_mul_f32_e32 v72, v72, v69
	v_mul_f32_e32 v72, v113, v72
	v_bfe_u32 v73, v72, 16, 1
	v_add3_u32 v72, v72, v73, s34
	ds_write_b16_d16_hi v171, v72 offset:544
	v_sub_f32_e32 v72, v94, v68
	v_mul_f32_e32 v72, v72, v69
	v_mul_f32_e32 v72, v3, v72
	v_bfe_u32 v73, v72, 16, 1
	v_add3_u32 v72, v72, v73, s34
	ds_write_b16_d16_hi v171, v72 offset:576
	v_sub_f32_e32 v72, v102, v68
	v_sub_f32_e32 v68, v70, v68
	v_mul_f32_e32 v72, v72, v69
	v_mul_f32_e32 v68, v68, v69
	v_mul_f32_e32 v72, v2, v72
	v_mul_f32_e32 v68, v1, v68
	v_bfe_u32 v73, v72, 16, 1
	v_bfe_u32 v69, v68, 16, 1
	v_add3_u32 v72, v72, v73, s34
	v_add3_u32 v68, v68, v69, s34
	ds_write_b16_d16_hi v171, v72 offset:608
	ds_write_b16_d16_hi v171, v68 offset:640
	ds_read_b64 v[68:69], v157
	s_waitcnt lgkmcnt(0)
	v_pk_add_f32 v[68:69], v[78:79], v[68:69]
	s_nop 0
	v_pk_mul_f32 v[68:69], v[68:69], s[20:21] op_sel_hi:[1,0]
	s_and_b64 s[20:21], vcc, exec
	v_fma_f32 v69, -v68, v68, v69
	v_max_f32_e32 v69, 0, v69
	v_add_f32_e32 v69, 0x3727c5ac, v69
	v_mul_f32_e32 v70, 0x4b800000, v69
	v_cmp_gt_f32_e64 s[44:45], s35, v69
	s_cselect_b32 s20, 0xffffffc0, s23
	s_lshl_b32 s26, s26, 4
	v_cndmask_b32_e64 v69, v69, v70, s[44:45]
	v_rsq_f32_e32 v69, v69
	s_addk_i32 s26, 0x3fd0
	s_add_i32 s25, s20, s25
	v_mul_f32_e32 v70, 0x45800000, v69
	v_cndmask_b32_e64 v69, v69, v70, s[44:45]
	v_sub_f32_e32 v70, v91, v68
	v_mul_f32_e32 v70, v70, v69
	v_mul_f32_e32 v70, v113, v70
	v_bfe_u32 v72, v70, 16, 1
	v_add3_u32 v70, v70, v72, s34
	ds_write_b16_d16_hi v171, v70 offset:816
	v_sub_f32_e32 v70, v95, v68
	v_mul_f32_e32 v70, v70, v69
	v_mul_f32_e32 v3, v3, v70
	v_bfe_u32 v70, v3, 16, 1
	v_add3_u32 v3, v3, v70, s34
	ds_write_b16_d16_hi v171, v3 offset:848
	v_sub_f32_e32 v3, v103, v68
	v_mul_f32_e32 v3, v3, v69
	v_mul_f32_e32 v2, v2, v3
	v_bfe_u32 v3, v2, 16, 1
	v_add3_u32 v2, v2, v3, s34
	ds_write_b16_d16_hi v171, v2 offset:880
	v_sub_f32_e32 v2, v71, v68
	v_mul_f32_e32 v2, v2, v69
	v_mul_f32_e32 v1, v1, v2
	v_bfe_u32 v2, v1, 16, 1
	v_add3_u32 v1, v1, v2, s34
	v_add_u32_e32 v2, s26, v123
	ds_write_b16_d16_hi v171, v1 offset:912
	v_add_u32_e32 v1, s25, v123
	v_cndmask_b32_e64 v2, -1, v2, s[0:1]
	v_cndmask_b32_e32 v68, v1, v2, vcc
	v_cmp_lt_i32_e64 s[44:45], -1, v68
	v_lshlrev_b32_e32 v2, 1, v122
	s_waitcnt lgkmcnt(0)
	s_barrier
	s_and_saveexec_b64 s[20:21], s[44:45]
	s_cbranch_execz .LBB0_416
	v_mov_b32_e32 v69, v0
	v_lshlrev_b64 v[68:69], 11, v[68:69]
	v_add_u32_e32 v1, v158, v127
	v_lshl_add_u64 v[72:73], s[4:5], 0, v[68:69]
	ds_read_b128 v[68:71], v1
	v_lshlrev_b32_e32 v76, 16, v40
	v_and_b32_e32 v77, 0xffff0000, v40
	s_lshl_b32 s58, s24, 1
	v_lshl_add_u64 v[72:73], v[72:73], 0, s[58:59]
	s_waitcnt lgkmcnt(0)
	v_lshlrev_b32_e32 v74, 16, v68
	v_and_b32_e32 v75, 0xffff0000, v68
	v_pk_mul_f32 v[74:75], v[76:77], v[74:75]
	v_lshlrev_b32_e32 v68, 16, v69
	v_cvt_pk_bf16_f32 v40, v74, v75
	v_and_b32_e32 v69, 0xffff0000, v69
	v_lshlrev_b32_e32 v74, 16, v41
	v_and_b32_e32 v75, 0xffff0000, v41
	v_pk_mul_f32 v[68:69], v[74:75], v[68:69]
	v_lshlrev_b32_e32 v74, 16, v42
	v_cvt_pk_bf16_f32 v41, v68, v69
	v_lshlrev_b32_e32 v68, 16, v70
	v_and_b32_e32 v69, 0xffff0000, v70
	v_and_b32_e32 v75, 0xffff0000, v42
	v_pk_mul_f32 v[68:69], v[74:75], v[68:69]
	v_lshlrev_b32_e32 v70, 16, v43
	v_cvt_pk_bf16_f32 v42, v68, v69
	v_lshlrev_b32_e32 v68, 16, v71
	v_and_b32_e32 v69, 0xffff0000, v71
	v_and_b32_e32 v71, 0xffff0000, v43
	v_mov_b32_e32 v3, v0
	v_pk_mul_f32 v[68:69], v[70:71], v[68:69]
	v_lshl_add_u64 v[72:73], v[72:73], 0, v[2:3]
	v_cvt_pk_bf16_f32 v43, v68, v69
	global_store_dwordx4 v[72:73], v[40:43], off offset:1024 sc1
.LBB0_416:
	s_or_b64 exec, exec, s[20:21]
	v_add_u32_e32 v3, s26, v124
	v_add_u32_e32 v1, s25, v124
	v_cndmask_b32_e64 v3, -1, v3, s[36:37]
	v_cndmask_b32_e32 v40, v1, v3, vcc
	v_cmp_lt_i32_e32 vcc, -1, v40
	s_and_saveexec_b64 s[20:21], vcc
	s_cbranch_execz .LBB0_393
	v_mov_b32_e32 v41, v0
	v_lshlrev_b64 v[40:41], 11, v[40:41]
	v_add_u32_e32 v1, v158, v128
	v_lshl_add_u64 v[68:69], s[4:5], 0, v[40:41]
	ds_read_b128 v[40:43], v1
	s_lshl_b32 s58, s24, 1
	v_lshl_add_u64 v[68:69], v[68:69], 0, s[58:59]
	v_mov_b32_e32 v3, v0
	v_lshl_add_u64 v[2:3], v[68:69], 0, v[2:3]
	s_waitcnt lgkmcnt(0)
	v_lshlrev_b32_e32 v68, 16, v40
	v_and_b32_e32 v69, 0xffff0000, v40
	v_lshlrev_b32_e32 v70, 16, v36
	v_and_b32_e32 v71, 0xffff0000, v36
	v_pk_mul_f32 v[68:69], v[70:71], v[68:69]
	v_lshlrev_b32_e32 v40, 16, v41
	v_cvt_pk_bf16_f32 v36, v68, v69
	v_and_b32_e32 v41, 0xffff0000, v41
	v_lshlrev_b32_e32 v68, 16, v37
	v_and_b32_e32 v69, 0xffff0000, v37
	v_pk_mul_f32 v[40:41], v[68:69], v[40:41]
	v_lshlrev_b32_e32 v68, 16, v38
	v_cvt_pk_bf16_f32 v37, v40, v41
	v_lshlrev_b32_e32 v40, 16, v42
	v_and_b32_e32 v41, 0xffff0000, v42
	v_and_b32_e32 v69, 0xffff0000, v38
	v_pk_mul_f32 v[40:41], v[68:69], v[40:41]
	v_lshlrev_b32_e32 v42, 16, v39
	v_cvt_pk_bf16_f32 v38, v40, v41
	v_lshlrev_b32_e32 v40, 16, v43
	v_and_b32_e32 v41, 0xffff0000, v43
	v_and_b32_e32 v43, 0xffff0000, v39
	v_pk_mul_f32 v[40:41], v[42:43], v[40:41]
	s_nop 0
	v_cvt_pk_bf16_f32 v39, v40, v41
	global_store_dwordx4 v[2:3], v[36:39], off offset:1024 sc1
	s_branch .LBB0_393

.LBB0_787:
	s_and_b64 s[12:13], s[16:17], exec
	s_movk_i32 s12, 0xb00
	s_cselect_b32 s77, s12, 0x400
	s_cmp_lg_u32 s33, 8
	v_readlane_b32 s14, v255, 5
	s_cselect_b64 s[12:13], -1, 0
	v_readlane_b32 s15, v255, 6
	s_or_b64 s[14:15], s[14:15], s[12:13]
	s_and_b64 s[12:13], s[16:17], exec
	s_cselect_b32 s5, s93, s5
	s_cselect_b32 s4, s92, s4
	s_and_b64 s[10:11], s[10:11], exec
	v_readlane_b32 s10, v254, 63
	v_readlane_b32 s12, v254, 61
	v_readlane_b32 s11, v255, 0
	v_readlane_b32 s13, v254, 62
	s_cselect_b32 s12, s12, s10
	s_cselect_b32 s13, s13, s11
	s_and_b64 s[10:11], s[16:17], exec
	v_readlane_b32 s10, v255, 9
	v_readlane_b32 s11, v255, 10
	s_cselect_b32 s11, s13, s11
	s_cselect_b32 s10, s12, s10
	s_and_b64 s[12:13], s[48:49], exec
	s_cselect_b32 s13, s69, s76
	s_cselect_b32 s12, s68, s63
	s_and_b64 vcc, exec, s[0:1]
	v_cndmask_b32_e64 v162, 1.0, 0.5, s[16:17]
	s_cbranch_vccnz .LBB0_907
	v_ashrrev_i32_e32 v4, 31, v2
	v_lshrrev_b32_e32 v4, 26, v4
	v_lshlrev_b32_e32 v3, 4, v2
	v_add_u32_e32 v4, v2, v4
	v_bfe_i32 v2, v2, 27, 1
	v_lshrrev_b32_e32 v2, 22, v2
	v_add_u32_e32 v2, v3, v2
	v_and_b32_e32 v2, 0xfffffc00, v2
	v_sub_u32_e32 v2, v3, v2
	v_lshrrev_b32_e32 v5, 4, v2
	v_bitop3_b32 v2, v5, v2, 32 bitop3:0x6c
	v_ashrrev_i32_e32 v6, 31, v2
	v_ashrrev_i32_e32 v4, 6, v4
	v_lshrrev_b32_e32 v6, 26, v6
	v_lshlrev_b32_e32 v5, 3, v4
	v_add_u32_e32 v6, v2, v6
	v_lshlrev_b32_e32 v4, 5, v4
	v_and_b32_e32 v5, 0x7ffffff0, v5
	v_ashrrev_i32_e32 v7, 6, v6
	v_and_b32_e32 v78, 32, v4
	v_and_b32_e32 v4, 0xc0, v6
	v_add_u32_e32 v5, v7, v5
	v_sub_u32_e32 v2, v2, v4
	v_ashrrev_i16_sdwa v2, v223, sext(v2) dst_sel:DWORD dst_unused:UNUSED_PAD src0_sel:DWORD src1_sel:BYTE_0
	v_mul_lo_u32 v80, v5, s77
	v_bfe_i32 v79, v2, 0, 16
	v_or_b32_e32 v2, v80, v78
	v_add_lshl_u32 v164, v2, v79, 1
	v_add_u32_e32 v2, 0x2000, v3
	v_ashrrev_i32_e32 v3, 31, v2
	v_lshrrev_b32_e32 v3, 22, v3
	v_add_u32_e32 v3, v2, v3
	v_ashrrev_i32_e32 v3, 10, v3
	v_mul_i32_i24_e32 v4, 0x400, v3
	v_sub_u32_e32 v2, v2, v4
	v_lshrrev_b32_e32 v4, 4, v2
	v_bitop3_b32 v2, v4, v2, 32 bitop3:0x6c
	v_ashrrev_i32_e32 v5, 31, v2
	v_lshrrev_b32_e32 v5, 26, v5
	s_ashr_i32 s24, s3, 8
	v_lshlrev_b32_e32 v4, 3, v3
	v_add_u32_e32 v5, v2, v5
	v_lshlrev_b32_e32 v3, 5, v3
	v_and_b32_e32 v4, 0x7ffffff0, v4
	v_ashrrev_i32_e32 v6, 6, v5
	v_and_b32_e32 v81, 32, v3
	v_and_b32_e32 v3, 0xc0, v5
	s_lshl_b32 s76, s24, 6
	s_lshl_b32 s0, s44, 8
	v_add_u32_e32 v4, v6, v4
	v_sub_u32_e32 v2, v2, v3
	s_add_i32 s0, s0, s76
	v_ashrrev_i16_sdwa v2, v223, sext(v2) dst_sel:DWORD dst_unused:UNUSED_PAD src0_sel:DWORD src1_sel:BYTE_0
	v_mul_lo_u32 v83, v4, s77
	v_and_or_b32 v10, v1, 63, s0
	s_ashr_i32 s22, s3, 6
	v_bfe_i32 v82, v2, 0, 16
	v_or_b32_e32 v2, v83, v81
	s_lshl_b32 s61, s77, 9
	v_ashrrev_i32_e32 v11, 31, v10
	v_add_lshl_u32 v166, v2, v82, 1
	s_lshl_b32 s16, s77, 8
	s_lshl_b32 s63, s22, 10
	v_lshlrev_b64 v[2:3], 7, v[10:11]
	v_add_u32_e32 v10, 0x80, v10
	s_mul_i32 s1, s61, s42
	v_ashrrev_i32_e32 v11, 31, v10
	s_mul_hi_i32 s0, s61, s42
	s_add_u32 s30, s10, s1
	v_lshlrev_b64 v[10:11], 7, v[10:11]
	s_addc_u32 s31, s11, s0
	s_add_i32 s87, s63, 0
	v_lshl_add_u64 v[2:3], s[94:95], 0, v[2:3]
	v_lshl_add_u64 v[10:11], s[94:95], 0, v[10:11]
	s_add_i32 m0, s87, 0x10000
	global_load_dwordx4 v[50:53], v[2:3], off
	global_load_dwordx4 v[42:45], v[2:3], off offset:16
	global_load_dwordx4 v[34:37], v[2:3], off offset:32
	global_load_dwordx4 v[26:29], v[2:3], off offset:48
	global_load_dwordx4 v[22:25], v[2:3], off offset:64
	global_load_dwordx4 v[18:21], v[2:3], off offset:80
	global_load_dwordx4 v[6:9], v[2:3], off offset:96
	s_nop 0
	global_load_dwordx4 v[2:5], v[2:3], off offset:112
	s_nop 0
	global_load_dwordx4 v[62:65], v[10:11], off
	global_load_dwordx4 v[58:61], v[10:11], off offset:16
	global_load_dwordx4 v[54:57], v[10:11], off offset:32
	global_load_dwordx4 v[46:49], v[10:11], off offset:48
	global_load_dwordx4 v[38:41], v[10:11], off offset:64
	global_load_dwordx4 v[30:33], v[10:11], off offset:80
	global_load_dwordx4 v[14:17], v[10:11], off offset:96
	s_nop 0
	global_load_dwordx4 v[10:13], v[10:11], off offset:112
	s_mul_i32 s19, s61, s44
	global_load_lds_dwordx4 v164, s[30:31]
	s_add_i32 m0, s87, 0x12000
	s_add_u32 s0, s30, s16
	global_load_lds_dwordx4 v166, s[30:31]
	s_addc_u32 s1, s31, 0
	s_add_i32 m0, s87, 0x14000
	s_mul_hi_i32 s18, s61, s44
	global_load_lds_dwordx4 v164, s[0:1]
	s_add_i32 m0, s87, 0x16000
	s_add_u32 s40, s4, s19
	v_mov_b32_e32 v165, v0
	v_mov_b32_e32 v167, v0
	s_addc_u32 s41, s5, s18
	s_add_i32 s82, s87, 0x2000
	v_lshl_add_u64 v[70:71], s[0:1], 0, v[164:165]
	v_lshl_add_u64 v[72:73], s[0:1], 0, v[166:167]
	global_load_lds_dwordx4 v166, s[0:1]
	v_readlane_b32 s18, v255, 11
	s_mov_b32 s19, 0
	s_cmp_eq_u32 s18, 2
	s_cselect_b32 s19, 22, s19
	s_cmp_eq_u32 s18, 9
	s_cselect_b32 s19, 44, s19
	s_cmp_eq_u32 s18, 11
	s_cselect_b32 s19, 66, s19
	s_cmp_eq_u32 s18, 18
	s_cselect_b32 s19, 88, s19
	s_cmp_eq_u32 s18, 7
	s_cselect_b32 s19, 8, s19
	s_cmp_eq_u32 s18, 16
	s_cselect_b32 s19, 16, s19
	s_cmp_eq_u32 s19, 0
	s_cbranch_scc1 .Lpanel_skip
	v_readlane_b32 s18, v254, 56
	s_cmp_lg_u32 s18, 0
	s_cbranch_scc1 .Lpanel_bar
	s_and_b32 s17, s55, 7
	s_lshl_b32 s17, s17, 5
	s_lshr_b32 s18, s55, 3
	s_add_u32 s17, s17, s18
	s_lshr_b32 s18, s17, 4
	s_lshl_b32 s18, s18, 2
	s_and_b32 s17, s17, 3
	s_or_b32 s17, s17, s18
	s_lshl_b32 s17, s17, 2
	s_movk_i32 s18, 0x3c00
	s_cmp_lt_u32 s19, 20
	s_cselect_b32 s18, 0x3e00, s18
	s_add_u32 s17, s17, s18
	v_mov_b32_e32 v84, s17
	s_mov_b32 s18, 0

.LBB0_907:
	s_andn2_b64 vcc, exec, s[14:15]
	s_cbranch_vccnz .LBB0_927
	s_add_i32 s0, s55, 0xa8
	s_ashr_i32 s1, s0, 31
	s_lshr_b32 s1, s1, 24
	s_add_i32 s1, s0, s1
	s_and_b32 s1, s1, 0xffffff00
	s_sub_i32 s15, s0, s1
	s_cmp_gt_i32 s15, 15
	v_mbcnt_lo_u32_b32 v1, -1, 0
	v_mbcnt_hi_u32_b32 v1, -1, v1
	s_cbranch_scc1 .LBB0_927
	s_waitcnt lgkmcnt(0)
	v_readlane_b32 s16, v255, 11
	s_mov_b32 s17, 0
	s_cmp_eq_u32 s16, 2
	s_cselect_b32 s17, 88, s17
	s_cmp_eq_u32 s16, 9
	s_cselect_b32 s17, 176, s17
	s_cmp_eq_u32 s16, 11
	s_cselect_b32 s17, 264, s17
	s_cmp_eq_u32 s16, 7
	s_cselect_b32 s17, 8, s17
	s_cmp_eq_u32 s16, 16
	s_cselect_b32 s17, 16, s17
	s_cmp_eq_u32 s17, 0
	s_cbranch_scc1 .Ltail_skip
	s_cmp_lg_u32 s86, 0
	s_cbranch_scc1 .Ltail_bar
	s_movk_i32 s16, 0x3d00
	s_cmp_lt_u32 s17, 20
	s_cselect_b32 s16, 0x3f00, s16
	v_mov_b32_e32 v2, s16
	s_mov_b32 s18, 0
